# v40 plus the first weight tile of phases 0 and 4 loaded the same way
# speedup vs baseline: 1.0276x; 1.0050x over previous
; template <bool NT = false>
; __device__ __forceinline__ void wconv_load(const WItem& t, f32x4 (&v)[8]) {
;     const int tid = threadIdx.x;
; #pragma unroll
;     for (int i = 0; i < 8; ++i) {
;         const int idx = tid + i * 512, kk = idx >> 6, c4 = (idx & 63) * 4;
;         v[i] = (f32x4){0.f, 0.f, 0.f, 0.f};
;         if (t.n0 + c4 + 3 < t.ncols) { const f32x4* sp = (const f32x4*)(t.src + (size_t)(t.k0 + kk) * t.ld + t.n0 + c4); v[i] = NT ? __builtin_nontemporal_load(sp) : *sp; }
;         if (t.gk) v[i] = v[i] * t.gk[t.k0 + kk];
;     }
; }
.LBB0_27:
	v_add_u32_e32 v0, s34, v52
	v_cmp_gt_i32_e64 s[4:5], s33, v0
	v_add_u32_e32 v98, s68, v168
	v_lshlrev_b32_e32 v112, 2, v41
	v_mov_b32_e32 v113, 0
	v_mov_b32_e32 v169, 0
	v_mov_b32_e32 v0, 0
	v_mov_b32_e32 v1, 0
	v_mov_b32_e32 v2, 0
	v_mov_b32_e32 v3, 0
	v_mov_b32_e32 v4, 0
	v_mov_b32_e32 v5, 0
	v_mov_b32_e32 v6, 0
	v_mov_b32_e32 v7, 0
	v_mov_b32_e32 v8, 0
	v_mov_b32_e32 v9, 0
	v_mov_b32_e32 v10, 0
	v_mov_b32_e32 v11, 0
	v_mov_b32_e32 v12, 0
	v_mov_b32_e32 v13, 0
	v_mov_b32_e32 v14, 0
	v_mov_b32_e32 v15, 0
	v_mov_b32_e32 v16, 0
	v_mov_b32_e32 v17, 0
	v_mov_b32_e32 v18, 0
	v_mov_b32_e32 v19, 0
	v_mov_b32_e32 v20, 0
	v_mov_b32_e32 v21, 0
	v_mov_b32_e32 v22, 0
	v_mov_b32_e32 v23, 0
	v_mov_b32_e32 v24, 0
	v_mov_b32_e32 v25, 0
	v_mov_b32_e32 v26, 0
	v_mov_b32_e32 v27, 0
	v_mov_b32_e32 v28, 0
	v_mov_b32_e32 v29, 0
	v_mov_b32_e32 v30, 0
	v_mov_b32_e32 v31, 0
	v_lshlrev_b32_e64 v100, 5, s33
	v_mov_b32_e32 v101, 0
	v_mov_b32_e32 v99, 0
	s_and_saveexec_b64 s[6:7], s[4:5]
	s_cbranch_execz .Lw0p_ld_done
	v_mad_u64_u32 v[96:97], s[8:9], v98, s33, 0
	v_lshl_add_u64 v[96:97], v[96:97], 2, s[30:31]
	s_ashr_i32 s35, s34, 31
	v_lshl_add_u64 v[96:97], s[34:35], 2, v[96:97]
	v_lshl_add_u64 v[96:97], v[96:97], 0, v[112:113]
	global_load_dwordx4 v[0:3], v[96:97], off
	v_lshl_add_u64 v[96:97], v[96:97], 0, v[100:101]
	global_load_dwordx4 v[4:7], v[96:97], off
	v_lshl_add_u64 v[96:97], v[96:97], 0, v[100:101]
	global_load_dwordx4 v[8:11], v[96:97], off
	v_lshl_add_u64 v[96:97], v[96:97], 0, v[100:101]
	global_load_dwordx4 v[12:15], v[96:97], off
	v_lshl_add_u64 v[96:97], v[96:97], 0, v[100:101]
	global_load_dwordx4 v[16:19], v[96:97], off
	v_lshl_add_u64 v[96:97], v[96:97], 0, v[100:101]
	global_load_dwordx4 v[20:23], v[96:97], off
	v_lshl_add_u64 v[96:97], v[96:97], 0, v[100:101]
	global_load_dwordx4 v[24:27], v[96:97], off
	v_lshl_add_u64 v[96:97], v[96:97], 0, v[100:101]
	global_load_dwordx4 v[28:31], v[96:97], off
.Lw0p_ld_done:
	s_or_b64 exec, exec, s[6:7]
	s_cmp_eq_u64 s[10:11], 0
	s_cbranch_scc1 .LBB0_59
	v_lshl_add_u64 v[102:103], v[98:99], 2, s[10:11]
	global_load_dword v104, v[102:103], off
	global_load_dword v105, v[102:103], off offset:32
	global_load_dword v106, v[102:103], off offset:64
	global_load_dword v107, v[102:103], off offset:96
	global_load_dword v108, v[102:103], off offset:128
	global_load_dword v109, v[102:103], off offset:160
	global_load_dword v110, v[102:103], off offset:192
	global_load_dword v111, v[102:103], off offset:224
	s_waitcnt vmcnt(0)
	v_mul_f32_e32 v0, v104, v0
	v_mul_f32_e32 v1, v104, v1
	v_mul_f32_e32 v2, v104, v2
	v_mul_f32_e32 v3, v104, v3
	v_mul_f32_e32 v4, v105, v4
	v_mul_f32_e32 v5, v105, v5
	v_mul_f32_e32 v6, v105, v6
	v_mul_f32_e32 v7, v105, v7
	v_mul_f32_e32 v8, v106, v8
	v_mul_f32_e32 v9, v106, v9
	v_mul_f32_e32 v10, v106, v10
	v_mul_f32_e32 v11, v106, v11
	v_mul_f32_e32 v12, v107, v12
	v_mul_f32_e32 v13, v107, v13
	v_mul_f32_e32 v14, v107, v14
	v_mul_f32_e32 v15, v107, v15
	v_mul_f32_e32 v16, v108, v16
	v_mul_f32_e32 v17, v108, v17
	v_mul_f32_e32 v18, v108, v18
	v_mul_f32_e32 v19, v108, v19
	v_mul_f32_e32 v20, v109, v20
	v_mul_f32_e32 v21, v109, v21
	v_mul_f32_e32 v22, v109, v22
	v_mul_f32_e32 v23, v109, v23
	v_mul_f32_e32 v24, v110, v24
	v_mul_f32_e32 v25, v110, v25
	v_mul_f32_e32 v26, v110, v26
	v_mul_f32_e32 v27, v110, v27
	v_mul_f32_e32 v28, v111, v28
	v_mul_f32_e32 v29, v111, v29
	v_mul_f32_e32 v30, v111, v30
	v_mul_f32_e32 v31, v111, v31

; template <bool NT = false>
; __device__ __forceinline__ void wconv_load(const WItem& t, f32x4 (&v)[8]) {
;     const int tid = threadIdx.x;
; #pragma unroll
;     for (int i = 0; i < 8; ++i) {
;         const int idx = tid + i * 512, kk = idx >> 6, c4 = (idx & 63) * 4;
;         v[i] = (f32x4){0.f, 0.f, 0.f, 0.f};
;         if (t.n0 + c4 + 3 < t.ncols) { const f32x4* sp = (const f32x4*)(t.src + (size_t)(t.k0 + kk) * t.ld + t.n0 + c4); v[i] = NT ? __builtin_nontemporal_load(sp) : *sp; }
;         if (t.gk) v[i] = v[i] * t.gk[t.k0 + kk];
;     }
; }
.LBB0_753:
	v_or3_b32 v0, v38, s12, 3
	v_cmp_gt_i32_e64 s[4:5], s18, v0
	v_add_u32_e32 v76, s16, v168
	v_lshlrev_b32_e32 v90, 2, v38
	v_mov_b32_e32 v91, 0
	v_mov_b32_e32 v169, 0
	v_mov_b32_e32 v0, 0
	v_mov_b32_e32 v1, 0
	v_mov_b32_e32 v2, 0
	v_mov_b32_e32 v3, 0
	v_mov_b32_e32 v4, 0
	v_mov_b32_e32 v5, 0
	v_mov_b32_e32 v6, 0
	v_mov_b32_e32 v7, 0
	v_mov_b32_e32 v8, 0
	v_mov_b32_e32 v9, 0
	v_mov_b32_e32 v10, 0
	v_mov_b32_e32 v11, 0
	v_mov_b32_e32 v12, 0
	v_mov_b32_e32 v13, 0
	v_mov_b32_e32 v14, 0
	v_mov_b32_e32 v15, 0
	v_mov_b32_e32 v16, 0
	v_mov_b32_e32 v17, 0
	v_mov_b32_e32 v18, 0
	v_mov_b32_e32 v19, 0
	v_mov_b32_e32 v20, 0
	v_mov_b32_e32 v21, 0
	v_mov_b32_e32 v22, 0
	v_mov_b32_e32 v23, 0
	v_mov_b32_e32 v24, 0
	v_mov_b32_e32 v25, 0
	v_mov_b32_e32 v26, 0
	v_mov_b32_e32 v27, 0
	v_mov_b32_e32 v28, 0
	v_mov_b32_e32 v29, 0
	v_mov_b32_e32 v30, 0
	v_mov_b32_e32 v31, 0
	v_lshlrev_b32_e64 v88, 5, s18
	v_mov_b32_e32 v89, 0
	v_mov_b32_e32 v77, 0
	s_and_saveexec_b64 s[6:7], s[4:5]
	s_cbranch_execz .Lw4p_ld_done
	v_mad_i64_i32 v[74:75], s[8:9], v76, s18, 0
	v_lshl_add_u64 v[74:75], v[74:75], 2, s[14:15]
	s_ashr_i32 s13, s12, 31
	v_lshl_add_u64 v[74:75], s[12:13], 2, v[74:75]
	v_lshl_add_u64 v[74:75], v[74:75], 0, v[90:91]
	global_load_dwordx4 v[0:3], v[74:75], off nt
	v_lshl_add_u64 v[74:75], v[74:75], 0, v[88:89]
	global_load_dwordx4 v[4:7], v[74:75], off nt
	v_lshl_add_u64 v[74:75], v[74:75], 0, v[88:89]
	global_load_dwordx4 v[8:11], v[74:75], off nt
	v_lshl_add_u64 v[74:75], v[74:75], 0, v[88:89]
	global_load_dwordx4 v[12:15], v[74:75], off nt
	v_lshl_add_u64 v[74:75], v[74:75], 0, v[88:89]
	global_load_dwordx4 v[16:19], v[74:75], off nt
	v_lshl_add_u64 v[74:75], v[74:75], 0, v[88:89]
	global_load_dwordx4 v[20:23], v[74:75], off nt
	v_lshl_add_u64 v[74:75], v[74:75], 0, v[88:89]
	global_load_dwordx4 v[24:27], v[74:75], off nt
	v_lshl_add_u64 v[74:75], v[74:75], 0, v[88:89]
	global_load_dwordx4 v[28:31], v[74:75], off nt
.Lw4p_ld_done:
	s_or_b64 exec, exec, s[6:7]
	s_cmp_eq_u64 s[10:11], 0
	s_cbranch_scc1 .LBB0_785
	v_lshl_add_u64 v[78:79], v[76:77], 2, s[10:11]
	global_load_dword v80, v[78:79], off
	global_load_dword v81, v[78:79], off offset:32
	global_load_dword v82, v[78:79], off offset:64
	global_load_dword v83, v[78:79], off offset:96
	global_load_dword v84, v[78:79], off offset:128
	global_load_dword v85, v[78:79], off offset:160
	global_load_dword v86, v[78:79], off offset:192
	global_load_dword v87, v[78:79], off offset:224
	s_waitcnt vmcnt(0)
	v_mul_f32_e32 v0, v80, v0
	v_mul_f32_e32 v1, v80, v1
	v_mul_f32_e32 v2, v80, v2
	v_mul_f32_e32 v3, v80, v3
	v_mul_f32_e32 v4, v81, v4
	v_mul_f32_e32 v5, v81, v5
	v_mul_f32_e32 v6, v81, v6
	v_mul_f32_e32 v7, v81, v7
	v_mul_f32_e32 v8, v82, v8
	v_mul_f32_e32 v9, v82, v9
	v_mul_f32_e32 v10, v82, v10
	v_mul_f32_e32 v11, v82, v11
	v_mul_f32_e32 v12, v83, v12
	v_mul_f32_e32 v13, v83, v13
	v_mul_f32_e32 v14, v83, v14
	v_mul_f32_e32 v15, v83, v15
	v_mul_f32_e32 v16, v84, v16
	v_mul_f32_e32 v17, v84, v17
	v_mul_f32_e32 v18, v84, v18
	v_mul_f32_e32 v19, v84, v19
	v_mul_f32_e32 v20, v85, v20
	v_mul_f32_e32 v21, v85, v21
	v_mul_f32_e32 v22, v85, v22
	v_mul_f32_e32 v23, v85, v23
	v_mul_f32_e32 v24, v86, v24
	v_mul_f32_e32 v25, v86, v25
	v_mul_f32_e32 v26, v86, v26
	v_mul_f32_e32 v27, v86, v27
	v_mul_f32_e32 v28, v87, v28
	v_mul_f32_e32 v29, v87, v29
	v_mul_f32_e32 v30, v87, v30
	v_mul_f32_e32 v31, v87, v31
